# UP phase: unit order permuted so the 44 sample-row tiles (slow epilogue) run first on the 5-unit WGs 172..215
# speedup vs baseline: 1.0184x; 1.0184x over previous
;     __device__ __forceinline__ bool next(int i, int& pm, int& pn, int& k0, int& nk, int& slice, int& src) const {
;         const long L = (long)i * G + c;
;         pm = 0; pn = 0; k0 = 0; nk = nt; slice = -1; src = 0;
;         if (L < nwg) {
;             int wgid = (int)L; { const int q = nwg / NXCD, r = nwg % NXCD, xcd = wgid % NXCD, off = wgid / NXCD; wgid = (xcd < r ? xcd * (q + 1) : r * (q + 1) + (xcd - r) * q) + off; }
;             const int nig = WGM * nN, gid = wgid / nig, fm = gid * WGM, gsz = (nM - fm) < WGM ? (nM - fm) : WGM;
;             pm = fm + ((wgid % nig) % gsz); pn = (wgid % nig) / gsz; return true;
; template <int EPI> ...
;     ...
;     if (!S.next(0, cur_pm, cur_pn, cur_k0, cur_nk, cur_slice, cur_src)) return;
.LBB0_951:
	s_or_b64 exec, exec, s[6:7]
	v_readlane_b32 s3, v244, 33
	s_waitcnt vmcnt(5)
	v_mov_b32_e32 v10, v0
	s_cmpk_lt_i32 s3, 0x5ac
	s_waitcnt lgkmcnt(0)
	s_barrier
	s_mov_b32 s54, 0
	v_readfirstlane_b32 s10, v10
	s_cselect_b64 s[6:7], -1, 0
	s_cmpk_gt_i32 s3, 0x5ab
	s_mov_b32 s18, 0
	s_cbranch_scc1 .LBB0_957
	v_readlane_b32 s0, v244, 59
	s_lshr_b32 s3, s0, 29
	v_readlane_b32 s9, v244, 33
	s_nop 3
	s_sub_u32 s98, s9, 172
	s_cmp_lt_u32 s98, 44
	s_cbranch_scc0 .Lperm7a_done
	s_lshl_b32 s98, s98, 3
	s_add_u32 s9, s98, 1103
.Lperm7a_done:
	s_add_i32 s3, s9, s3
	s_and_b32 s8, s3, -8
	s_sub_i32 s11, s9, s8
	s_cmp_gt_i32 s11, 3
	s_cbranch_scc0 .LBB0_954
	s_mul_i32 s8, s11, 0xb5
	s_add_i32 s12, s8, 4
	s_cbranch_execz .LBB0_955
	s_branch .LBB0_956

;     __device__ __forceinline__ bool next(int i, int& pm, int& pn, int& k0, int& nk, int& slice, int& src) const {
;         const long L = (long)i * G + c;
;         pm = 0; pn = 0; k0 = 0; nk = nt; slice = -1; src = 0;
;         if (L < nwg) {
;             int wgid = (int)L; { const int q = nwg / NXCD, r = nwg % NXCD, xcd = wgid % NXCD, off = wgid / NXCD; wgid = (xcd < r ? xcd * (q + 1) : r * (q + 1) + (xcd - r) * q) + off; }
;             const int nig = WGM * nN, gid = wgid / nig, fm = gid * WGM, gsz = (nM - fm) < WGM ? (nM - fm) : WGM;
;             pm = fm + ((wgid % nig) % gsz); pn = (wgid % nig) / gsz; return true;
; template <int EPI> ...
;     ...
;         const bool has_next = S.next(ui + 1, nxt_pm, nxt_pn, nxt_k0, nxt_nk, nxt_slice, nxt_src);
.LBB0_963:
	s_add_i32 s70, s70, 1
	s_mul_i32 s16, s70, s74
	s_mul_hi_u32 s17, s70, s33
	s_add_i32 s17, s17, s16
	s_mul_i32 s16, s70, s33
	v_readlane_b32 s19, v244, 33
	s_add_u32 s50, s16, s19
	v_readlane_b32 s16, v244, 59
	s_addc_u32 s51, s17, s16
	v_cmp_gt_i64_e32 vcc, s[50:51], v[212:213]
	v_cmp_lt_i64_e64 s[16:17], s[50:51], v[210:211]
	s_mov_b32 s46, 0
	s_mov_b32 s48, 0
	s_cbranch_vccnz .LBB0_969
	s_sub_u32 s98, s50, 172
	s_cmp_lt_u32 s98, 44
	s_cbranch_scc0 .Lperm7b_1
	s_lshl_b32 s98, s98, 3
	s_add_u32 s50, s98, 1103
	s_branch .Lperm7b_done
.Lperm7b_1:
	s_sub_u32 s98, s50, 1103
	s_cmp_lt_u32 s98, 345
	s_cbranch_scc0 .Lperm7b_done
	s_and_b32 s99, s98, 7
	s_cmp_eq_u32 s99, 0
	s_cbranch_scc0 .Lperm7b_done
	s_lshr_b32 s98, s98, 3
	s_add_u32 s50, s98, 172
.Lperm7b_done:
	s_ashr_i32 s19, s50, 31
	s_lshr_b32 s19, s19, 29
	s_add_i32 s19, s50, s19
	s_and_b32 s46, s19, -8
	s_sub_i32 s48, s50, s46
	s_cmp_gt_i32 s48, 3
	s_mov_b64 s[46:47], -1
	s_cbranch_scc0 .LBB0_966
	s_mul_i32 s46, s48, 0xb5
	s_add_i32 s49, s46, 4
	s_mov_b64 s[46:47], 0
